# v039 g5 converter CUs: 2 items in flight per wave + leftover gate/up items of layers 2,3 (prologue sheds 215 MB)
# speedup vs baseline: 1.0041x; 1.0041x over previous
; DEV void phase_prologue_a(const Frame& F0) {
;     ...
;         constexpr int GU_NB = 2 * FF / 32, GU_ITEMS = 16 * GU_NB;
;         for (int it = F.gw; it < NE * GU_ITEMS; it += F.NGW) { const int e = it / GU_ITEMS, r = it % GU_ITEMS, kb = r / GU_NB, nb = r % GU_NB; const int d0 = 32 * nb, j = d0 >> 8, w = d0 & 255;
;             const float* src = (w < 128 ? GIN(I_WGATE) : GIN(I_WUP)) + ((size_t)l * NE + e) * 1024 * FF;
;             tr_item(src, FF, 128 * j + (w & 127), 64 * kb, (bf16_t*)(F.ws + WS_WGU) + ((size_t)l * NE + e) * 2 * FF * 1024, 1024, d0, scr, F.lane); }
.LBB0_24:
	s_andn2_b64 vcc, exec, s[10:11]
	s_cbranch_vccnz .LBB0_29
	s_lshl_b64 s[20:21], s[2:3], 27
	s_mov_b32 s28, s31
	s_cmp_eq_u32 s14, 0
	s_cbranch_scc1 .Lpro_gu_all
	v_readlane_b32 s100, v255, 51
	s_cmp_lg_u32 s100, 0x100
	s_cbranch_scc1 .Lpro_gu_all
	s_cmp_eq_u32 s14, 1
	s_cbranch_scc1 .LBB0_29
	s_cmp_eq_u32 s14, 2
	s_cbranch_scc1 .LBB0_29
	s_mov_b32 s100, 0x6500
	s_add_i32 s28, s28, s100

; #define LAS __attribute__((address_space(3)))
; #define NT_LOAD(p) __builtin_nontemporal_load(p)
; DEV void tr_item(const float* W, int ldw, int col0, int k0, bf16_t* WT, int K, int row0, LAS float* scr, int lane) {
; #pragma unroll 8
;     for (int i = 0; i < 32; ++i) { const int kk = 2 * i + (lane >> 5); scr[kk * 33 + (lane & 31)] = NT_LOAD(&W[(size_t)(k0 + kk) * ldw + col0 + (lane & 31)]); }
; DEV void phase_prologue_a(const Frame& F0) {
;     ...
;         constexpr int D_ITEMS = (FF / 64) * 32;
;         for (int it = F.gw; it < NE * D_ITEMS; it += F.NGW) { const int e = it / D_ITEMS, r = it % D_ITEMS, kb = r / 32, nb = r % 32;
;             tr_item(GIN(I_WDOWN) + ((size_t)l * NE + e) * FF * 1024, 1024, 32 * nb, 64 * kb, (bf16_t*)(F.ws + WS_WD) + ((size_t)l * NE + e) * 1024 * FF, FF, 32 * nb, scr, F.lane); }
.Lsd_loop:
	s_lshr_b32 s8, s2, 10
	s_and_b32 s9, s2, 0x3ff
	s_lshr_b32 s10, s9, 5
	s_and_b32 s9, s9, 31
	s_lshl_b32 s24, s10, 18
	s_lshl_b32 s25, s9, 7
	s_add_i32 s24, s24, s25
	s_lshr_b32 s29, s8, 9
	s_lshl_b32 s28, s8, 23
	s_add_u32 s28, s28, s24
	s_addc_u32 s29, s29, 0
	s_add_u32 s28, s28, s4
	s_addc_u32 s29, s29, s5
	s_lshl_b32 s24, s9, 17
	s_lshl_b32 s25, s10, 7
	s_add_i32 s24, s24, s25
	s_lshr_b32 s11, s8, 10
	s_lshl_b32 s10, s8, 22
	s_add_u32 s10, s10, s24
	s_addc_u32 s11, s11, 0
	s_add_u32 s10, s10, s6
	s_addc_u32 s11, s11, s7
	v_lshl_add_u64 v[16:17], s[28:29], 0, v[122:123]
	v_lshl_add_u64 v[18:19], v[16:17], 0, s[44:45]
	v_lshl_add_u64 v[20:21], v[18:19], 0, s[44:45]
	v_lshl_add_u64 v[22:23], v[20:21], 0, s[44:45]
	v_lshl_add_u64 v[24:25], v[22:23], 0, s[44:45]
	v_lshl_add_u64 v[26:27], v[24:25], 0, s[44:45]
	v_lshl_add_u64 v[28:29], v[26:27], 0, s[44:45]
	v_lshl_add_u64 v[30:31], v[28:29], 0, s[44:45]
	global_load_dword v32, v[16:17], off nt
	global_load_dword v33, v[18:19], off nt
	global_load_dword v34, v[20:21], off nt
	global_load_dword v35, v[22:23], off nt
	global_load_dword v36, v[24:25], off nt
	global_load_dword v37, v[26:27], off nt
	global_load_dword v38, v[28:29], off nt
	global_load_dword v39, v[30:31], off nt
	v_lshl_add_u64 v[16:17], v[16:17], 0, s[40:41]
	v_lshl_add_u64 v[18:19], v[18:19], 0, s[40:41]
	v_lshl_add_u64 v[20:21], v[20:21], 0, s[40:41]
	v_lshl_add_u64 v[22:23], v[22:23], 0, s[40:41]
	v_lshl_add_u64 v[24:25], v[24:25], 0, s[40:41]
	v_lshl_add_u64 v[26:27], v[26:27], 0, s[40:41]
	v_lshl_add_u64 v[28:29], v[28:29], 0, s[40:41]
	v_lshl_add_u64 v[30:31], v[30:31], 0, s[40:41]
	global_load_dword v40, v[16:17], off nt
	global_load_dword v41, v[18:19], off nt
	global_load_dword v42, v[20:21], off nt
	global_load_dword v43, v[22:23], off nt
	global_load_dword v44, v[24:25], off nt
	global_load_dword v45, v[26:27], off nt
	global_load_dword v46, v[28:29], off nt
	global_load_dword v47, v[30:31], off nt
	v_lshl_add_u64 v[16:17], v[16:17], 0, s[40:41]
	v_lshl_add_u64 v[18:19], v[18:19], 0, s[40:41]
	v_lshl_add_u64 v[20:21], v[20:21], 0, s[40:41]
	v_lshl_add_u64 v[22:23], v[22:23], 0, s[40:41]
	v_lshl_add_u64 v[24:25], v[24:25], 0, s[40:41]
	v_lshl_add_u64 v[26:27], v[26:27], 0, s[40:41]
	v_lshl_add_u64 v[28:29], v[28:29], 0, s[40:41]
	v_lshl_add_u64 v[30:31], v[30:31], 0, s[40:41]
	global_load_dword v48, v[16:17], off nt
	global_load_dword v49, v[18:19], off nt
	global_load_dword v50, v[20:21], off nt
	global_load_dword v51, v[22:23], off nt
	global_load_dword v52, v[24:25], off nt
	global_load_dword v53, v[26:27], off nt
	global_load_dword v54, v[28:29], off nt
	global_load_dword v55, v[30:31], off nt
	v_lshl_add_u64 v[16:17], v[16:17], 0, s[40:41]
	v_lshl_add_u64 v[18:19], v[18:19], 0, s[40:41]
	v_lshl_add_u64 v[20:21], v[20:21], 0, s[40:41]
	v_lshl_add_u64 v[22:23], v[22:23], 0, s[40:41]
	v_lshl_add_u64 v[24:25], v[24:25], 0, s[40:41]
	v_lshl_add_u64 v[26:27], v[26:27], 0, s[40:41]
	v_lshl_add_u64 v[28:29], v[28:29], 0, s[40:41]
	v_lshl_add_u64 v[30:31], v[30:31], 0, s[40:41]
	global_load_dword v56, v[16:17], off nt
	global_load_dword v57, v[18:19], off nt
	global_load_dword v58, v[20:21], off nt
	global_load_dword v59, v[22:23], off nt
	global_load_dword v60, v[24:25], off nt
	global_load_dword v61, v[26:27], off nt
	global_load_dword v62, v[28:29], off nt
	global_load_dword v63, v[30:31], off nt
	v_lshl_add_u64 v[64:65], s[10:11], 0, v[124:125]
	v_lshl_add_u64 v[66:67], v[64:65], 0, s[42:43]
	v_lshl_add_u64 v[68:69], v[66:67], 0, s[42:43]
	v_lshl_add_u64 v[70:71], v[68:69], 0, s[42:43]
	s_add_i32 s31, s2, 0x200
	s_lshr_b32 s8, s31, 10
	s_and_b32 s9, s31, 0x3ff
	s_lshr_b32 s10, s9, 5
	s_and_b32 s9, s9, 31
	s_lshl_b32 s24, s10, 18
	s_lshl_b32 s25, s9, 7
	s_add_i32 s24, s24, s25
	s_lshr_b32 s29, s8, 9
	s_lshl_b32 s28, s8, 23
	s_add_u32 s28, s28, s24
	s_addc_u32 s29, s29, 0
	s_add_u32 s28, s28, s4
	s_addc_u32 s29, s29, s5
	s_lshl_b32 s24, s9, 17
	s_lshl_b32 s25, s10, 7
	s_add_i32 s24, s24, s25
	s_lshr_b32 s11, s8, 10
	s_lshl_b32 s10, s8, 22
	s_add_u32 s10, s10, s24
	s_addc_u32 s11, s11, 0
	s_add_u32 s10, s10, s6
	s_addc_u32 s11, s11, s7
	v_lshl_add_u64 v[16:17], s[28:29], 0, v[122:123]
	v_lshl_add_u64 v[18:19], v[16:17], 0, s[44:45]
	v_lshl_add_u64 v[20:21], v[18:19], 0, s[44:45]
	v_lshl_add_u64 v[22:23], v[20:21], 0, s[44:45]
	v_lshl_add_u64 v[24:25], v[22:23], 0, s[44:45]
	v_lshl_add_u64 v[26:27], v[24:25], 0, s[44:45]
	v_lshl_add_u64 v[28:29], v[26:27], 0, s[44:45]
	v_lshl_add_u64 v[30:31], v[28:29], 0, s[44:45]
	global_load_dword v126, v[16:17], off nt
	global_load_dword v127, v[18:19], off nt
	global_load_dword v128, v[20:21], off nt
	global_load_dword v129, v[22:23], off nt
	global_load_dword v130, v[24:25], off nt
	global_load_dword v131, v[26:27], off nt
	global_load_dword v132, v[28:29], off nt
	global_load_dword v133, v[30:31], off nt
	v_lshl_add_u64 v[16:17], v[16:17], 0, s[40:41]
	v_lshl_add_u64 v[18:19], v[18:19], 0, s[40:41]
	v_lshl_add_u64 v[20:21], v[20:21], 0, s[40:41]
	v_lshl_add_u64 v[22:23], v[22:23], 0, s[40:41]
	v_lshl_add_u64 v[24:25], v[24:25], 0, s[40:41]
	v_lshl_add_u64 v[26:27], v[26:27], 0, s[40:41]
	v_lshl_add_u64 v[28:29], v[28:29], 0, s[40:41]
	v_lshl_add_u64 v[30:31], v[30:31], 0, s[40:41]
	global_load_dword v134, v[16:17], off nt
	global_load_dword v135, v[18:19], off nt
	global_load_dword v136, v[20:21], off nt
	global_load_dword v137, v[22:23], off nt
	global_load_dword v138, v[24:25], off nt
	global_load_dword v139, v[26:27], off nt
	global_load_dword v140, v[28:29], off nt
	global_load_dword v141, v[30:31], off nt
	v_lshl_add_u64 v[16:17], v[16:17], 0, s[40:41]
; #define WAVE_LDS_SYNC() do { int _z = 0; (void)emu::wave_xchg(&_z, 4); } while (0)
; #define LAS __attribute__((address_space(3)))
; #define WAVE_LDS_SYNC() asm volatile("s_waitcnt lgkmcnt(0)" ::: "memory")
; #define NT_LOAD(p) __builtin_nontemporal_load(p)
; #define NT_STORE(v, p) __builtin_nontemporal_store((v), (p))
; DEV unsigned pk2(float lo, float hi) { return f2bf(lo) | (f2bf(hi) << 16); }
; DEV unsigned pk2(float lo, float hi) { const f32x2n_t v = {lo, hi}; return __builtin_bit_cast(unsigned, __builtin_convertvector(v, bf16x2n_t)); }
; DEV void tr_item(const float* W, int ldw, int col0, int k0, bf16_t* WT, int K, int row0, LAS float* scr, int lane) {
; #pragma unroll 8
;     for (int i = 0; i < 32; ++i) { const int kk = 2 * i + (lane >> 5); scr[kk * 33 + (lane & 31)] = NT_LOAD(&W[(size_t)(k0 + kk) * ldw + col0 + (lane & 31)]); }
;     WAVE_LDS_SYNC();
;     const int c = lane & 7;
; #pragma unroll
;     for (int j = 0; j < 4; ++j) { const int n = (lane >> 3) + 8 * j; const LAS float* s = scr + (8 * c) * 33 + n;
;         u32x4 o; o.x = pk2(s[0 * 33], s[1 * 33]); o.y = pk2(s[2 * 33], s[3 * 33]); o.z = pk2(s[4 * 33], s[5 * 33]); o.w = pk2(s[6 * 33], s[7 * 33]);
;         NT_STORE(o, (u32x4*)(WT + (size_t)(row0 + n) * K + k0 + 8 * c)); }
	v_lshl_add_u64 v[18:19], v[18:19], 0, s[40:41]
	v_lshl_add_u64 v[20:21], v[20:21], 0, s[40:41]
	v_lshl_add_u64 v[22:23], v[22:23], 0, s[40:41]
	v_lshl_add_u64 v[24:25], v[24:25], 0, s[40:41]
	v_lshl_add_u64 v[26:27], v[26:27], 0, s[40:41]
	v_lshl_add_u64 v[28:29], v[28:29], 0, s[40:41]
	v_lshl_add_u64 v[30:31], v[30:31], 0, s[40:41]
	global_load_dword v142, v[16:17], off nt
	global_load_dword v143, v[18:19], off nt
	global_load_dword v144, v[20:21], off nt
	global_load_dword v145, v[22:23], off nt
	global_load_dword v150, v[24:25], off nt
	global_load_dword v151, v[26:27], off nt
	global_load_dword v152, v[28:29], off nt
	global_load_dword v153, v[30:31], off nt
	v_lshl_add_u64 v[16:17], v[16:17], 0, s[40:41]
	v_lshl_add_u64 v[18:19], v[18:19], 0, s[40:41]
	v_lshl_add_u64 v[20:21], v[20:21], 0, s[40:41]
	v_lshl_add_u64 v[22:23], v[22:23], 0, s[40:41]
	v_lshl_add_u64 v[24:25], v[24:25], 0, s[40:41]
	v_lshl_add_u64 v[26:27], v[26:27], 0, s[40:41]
	v_lshl_add_u64 v[28:29], v[28:29], 0, s[40:41]
	v_lshl_add_u64 v[30:31], v[30:31], 0, s[40:41]
	global_load_dword v154, v[16:17], off nt
	global_load_dword v155, v[18:19], off nt
	global_load_dword v156, v[20:21], off nt
	global_load_dword v157, v[22:23], off nt
	global_load_dword v158, v[24:25], off nt
	global_load_dword v159, v[26:27], off nt
	global_load_dword v160, v[28:29], off nt
	global_load_dword v161, v[30:31], off nt
	v_lshl_add_u64 v[162:163], s[10:11], 0, v[124:125]
	v_lshl_add_u64 v[164:165], v[162:163], 0, s[42:43]
	v_lshl_add_u64 v[166:167], v[164:165], 0, s[42:43]
	v_lshl_add_u64 v[168:169], v[166:167], 0, s[42:43]
	s_waitcnt vmcnt(62)
	ds_write2_b32 v7, v32, v33 offset1:66
	s_waitcnt vmcnt(60)
	ds_write2_b32 v7, v34, v35 offset0:132 offset1:198
	s_waitcnt vmcnt(58)
	ds_write2_b32 v8, v36, v37 offset0:8 offset1:74
	s_waitcnt vmcnt(56)
	ds_write2_b32 v8, v38, v39 offset0:140 offset1:206
	s_waitcnt vmcnt(54)
	ds_write2_b32 v9, v40, v41 offset1:66
	s_waitcnt vmcnt(52)
	ds_write2_b32 v9, v42, v43 offset0:132 offset1:198
	s_waitcnt vmcnt(50)
	ds_write2_b32 v10, v44, v45 offset0:8 offset1:74
	s_waitcnt vmcnt(48)
	ds_write2_b32 v10, v46, v47 offset0:140 offset1:206
	s_waitcnt vmcnt(46)
	ds_write2_b32 v11, v48, v49 offset1:66
	s_waitcnt vmcnt(44)
	ds_write2_b32 v11, v50, v51 offset0:132 offset1:198
	s_waitcnt vmcnt(42)
	ds_write2_b32 v12, v52, v53 offset0:8 offset1:74
	s_waitcnt vmcnt(40)
	ds_write2_b32 v12, v54, v55 offset0:140 offset1:206
	s_waitcnt vmcnt(38)
	ds_write2_b32 v13, v56, v57 offset1:66
	s_waitcnt vmcnt(36)
	ds_write2_b32 v13, v58, v59 offset0:132 offset1:198
	s_waitcnt vmcnt(34)
	ds_write2_b32 v14, v60, v61 offset0:8 offset1:74
	s_waitcnt vmcnt(32)
	ds_write2_b32 v14, v62, v63 offset0:140 offset1:206
	ds_read2_b32 v[72:73], v15 offset1:8
	ds_read2_b32 v[74:75], v15 offset0:33 offset1:41
	ds_read2_b32 v[76:77], v15 offset0:66 offset1:74
	ds_read2_b32 v[78:79], v15 offset0:99 offset1:107
	ds_read2_b32 v[80:81], v15 offset0:132 offset1:140
	ds_read2_b32 v[82:83], v15 offset0:165 offset1:173
	ds_read2_b32 v[84:85], v15 offset0:198 offset1:206
	ds_read2_b32 v[86:87], v15 offset0:231 offset1:239
	ds_read2_b32 v[88:89], v15 offset0:16 offset1:24
	ds_read2_b32 v[90:91], v15 offset0:49 offset1:57
	ds_read2_b32 v[92:93], v15 offset0:82 offset1:90
	ds_read2_b32 v[94:95], v15 offset0:115 offset1:123
	s_waitcnt lgkmcnt(4)
	v_cvt_pk_bf16_f32 v104, v72, v74
	v_cvt_pk_bf16_f32 v105, v76, v78
	v_cvt_pk_bf16_f32 v106, v80, v82
	v_cvt_pk_bf16_f32 v107, v84, v86
	v_cvt_pk_bf16_f32 v108, v73, v75
	v_cvt_pk_bf16_f32 v109, v77, v79
	v_cvt_pk_bf16_f32 v110, v81, v83
	v_cvt_pk_bf16_f32 v111, v85, v87
	ds_read2_b32 v[96:97], v15 offset0:148 offset1:156
	ds_read2_b32 v[98:99], v15 offset0:181 offset1:189
	ds_read2_b32 v[100:101], v15 offset0:214 offset1:222
	ds_read2_b32 v[102:103], v15 offset0:247 offset1:255
	global_store_dwordx4 v[64:65], v[104:107], off nt
	global_store_dwordx4 v[66:67], v[108:111], off nt
	s_waitcnt lgkmcnt(0)
	v_cvt_pk_bf16_f32 v112, v88, v90
	v_cvt_pk_bf16_f32 v113, v92, v94
	v_cvt_pk_bf16_f32 v114, v96, v98
	v_cvt_pk_bf16_f32 v115, v100, v102
	v_cvt_pk_bf16_f32 v116, v89, v91
	v_cvt_pk_bf16_f32 v117, v93, v95
	v_cvt_pk_bf16_f32 v118, v97, v99
	v_cvt_pk_bf16_f32 v119, v101, v103
	global_store_dwordx4 v[68:69], v[112:115], off nt
	global_store_dwordx4 v[70:71], v[116:119], off nt
	s_waitcnt vmcnt(34)
	ds_write2_b32 v7, v126, v127 offset1:66
	s_waitcnt vmcnt(32)
	ds_write2_b32 v7, v128, v129 offset0:132 offset1:198
	s_waitcnt vmcnt(30)
	ds_write2_b32 v8, v130, v131 offset0:8 offset1:74
	s_waitcnt vmcnt(28)
	ds_write2_b32 v8, v132, v133 offset0:140 offset1:206
	s_waitcnt vmcnt(26)
	ds_write2_b32 v9, v134, v135 offset1:66
	s_waitcnt vmcnt(24)
	ds_write2_b32 v9, v136, v137 offset0:132 offset1:198
	s_waitcnt vmcnt(22)
	ds_write2_b32 v10, v138, v139 offset0:8 offset1:74
	s_waitcnt vmcnt(20)
	ds_write2_b32 v10, v140, v141 offset0:140 offset1:206
	s_waitcnt vmcnt(18)
	ds_write2_b32 v11, v142, v143 offset1:66
	s_waitcnt vmcnt(16)
	ds_write2_b32 v11, v144, v145 offset0:132 offset1:198
	s_waitcnt vmcnt(14)
	ds_write2_b32 v12, v150, v151 offset0:8 offset1:74
	s_waitcnt vmcnt(12)
	ds_write2_b32 v12, v152, v153 offset0:140 offset1:206
	s_waitcnt vmcnt(10)
	ds_write2_b32 v13, v154, v155 offset1:66
	s_waitcnt vmcnt(8)
	ds_write2_b32 v13, v156, v157 offset0:132 offset1:198
	s_waitcnt vmcnt(6)
	ds_write2_b32 v14, v158, v159 offset0:8 offset1:74
	s_waitcnt vmcnt(4)
; #define LAS __attribute__((address_space(3)))
; #define NT_STORE(v, p) __builtin_nontemporal_store((v), (p))
; DEV unsigned pk2(float lo, float hi) { return f2bf(lo) | (f2bf(hi) << 16); }
; DEV unsigned pk2(float lo, float hi) { const f32x2n_t v = {lo, hi}; return __builtin_bit_cast(unsigned, __builtin_convertvector(v, bf16x2n_t)); }
; DEV void tr_item(const float* W, int ldw, int col0, int k0, bf16_t* WT, int K, int row0, LAS float* scr, int lane) {
;     ...
;     for (int j = 0; j < 4; ++j) { const int n = (lane >> 3) + 8 * j; const LAS float* s = scr + (8 * c) * 33 + n;
;         u32x4 o; o.x = pk2(s[0 * 33], s[1 * 33]); o.y = pk2(s[2 * 33], s[3 * 33]); o.z = pk2(s[4 * 33], s[5 * 33]); o.w = pk2(s[6 * 33], s[7 * 33]);
;         NT_STORE(o, (u32x4*)(WT + (size_t)(row0 + n) * K + k0 + 8 * c)); }
; DEV void phase_prologue_a(const Frame& F0) {
;     ...
;         constexpr int GU_NB = 2 * FF / 32, GU_ITEMS = 16 * GU_NB;
;         for (int it = F.gw; it < NE * GU_ITEMS; it += F.NGW) { const int e = it / GU_ITEMS, r = it % GU_ITEMS, kb = r / GU_NB, nb = r % GU_NB; const int d0 = 32 * nb, j = d0 >> 8, w = d0 & 255;
;             const float* src = (w < 128 ? GIN(I_WGATE) : GIN(I_WUP)) + ((size_t)l * NE + e) * 1024 * FF;
;             tr_item(src, FF, 128 * j + (w & 127), 64 * kb, (bf16_t*)(F.ws + WS_WGU) + ((size_t)l * NE + e) * 2 * FF * 1024, 1024, d0, scr, F.lane); }
	ds_write2_b32 v14, v160, v161 offset0:140 offset1:206
	ds_read2_b32 v[72:73], v15 offset1:8
	ds_read2_b32 v[74:75], v15 offset0:33 offset1:41
	ds_read2_b32 v[76:77], v15 offset0:66 offset1:74
	ds_read2_b32 v[78:79], v15 offset0:99 offset1:107
	ds_read2_b32 v[80:81], v15 offset0:132 offset1:140
	ds_read2_b32 v[82:83], v15 offset0:165 offset1:173
	ds_read2_b32 v[84:85], v15 offset0:198 offset1:206
	ds_read2_b32 v[86:87], v15 offset0:231 offset1:239
	ds_read2_b32 v[88:89], v15 offset0:16 offset1:24
	ds_read2_b32 v[90:91], v15 offset0:49 offset1:57
	ds_read2_b32 v[92:93], v15 offset0:82 offset1:90
	ds_read2_b32 v[94:95], v15 offset0:115 offset1:123
	s_waitcnt lgkmcnt(4)
	v_cvt_pk_bf16_f32 v104, v72, v74
	v_cvt_pk_bf16_f32 v105, v76, v78
	v_cvt_pk_bf16_f32 v106, v80, v82
	v_cvt_pk_bf16_f32 v107, v84, v86
	v_cvt_pk_bf16_f32 v108, v73, v75
	v_cvt_pk_bf16_f32 v109, v77, v79
	v_cvt_pk_bf16_f32 v110, v81, v83
	v_cvt_pk_bf16_f32 v111, v85, v87
	ds_read2_b32 v[96:97], v15 offset0:148 offset1:156
	ds_read2_b32 v[98:99], v15 offset0:181 offset1:189
	ds_read2_b32 v[100:101], v15 offset0:214 offset1:222
	ds_read2_b32 v[102:103], v15 offset0:247 offset1:255
	global_store_dwordx4 v[162:163], v[104:107], off nt
	global_store_dwordx4 v[164:165], v[108:111], off nt
	s_waitcnt lgkmcnt(0)
	v_cvt_pk_bf16_f32 v112, v88, v90
	v_cvt_pk_bf16_f32 v113, v92, v94
	v_cvt_pk_bf16_f32 v114, v96, v98
	v_cvt_pk_bf16_f32 v115, v100, v102
	v_cvt_pk_bf16_f32 v116, v89, v91
	v_cvt_pk_bf16_f32 v117, v93, v95
	v_cvt_pk_bf16_f32 v118, v97, v99
	v_cvt_pk_bf16_f32 v119, v101, v103
	global_store_dwordx4 v[166:167], v[112:115], off nt
	global_store_dwordx4 v[168:169], v[116:119], off nt
	s_addk_i32 s2, 0x400
	s_cmp_lt_u32 s2, 0x4000
	s_cbranch_scc1 .Lsd_loop
	s_mov_b32 s36, 2
	s_mov_b32 s37, 0x5200
	s_mov_b32 s101, 0x6a00
	s_cmp_eq_u32 s0, 1
	s_cbranch_scc1 .Lsx_go
	s_mov_b32 s37, 0x6a00
	s_mov_b32 s101, 0x8000
	s_cmp_eq_u32 s0, 2
	s_cbranch_scc1 .Lsx_go
	s_mov_b32 s36, 3
	s_mov_b32 s37, 0x4d00
	s_mov_b32 s101, 0x6500
.Lsx_go:
	v_readlane_b32 s2, v255, 48
	v_readlane_b32 s3, v251, 29
	s_sub_i32 s2, s2, 0xc0
	s_lshl_b32 s2, s2, 3
	s_add_i32 s2, s2, s3
	s_add_i32 s2, s2, s37
	v_readlane_b32 s6, v255, 53
	v_readlane_b32 s7, v255, 54
	v_readlane_b32 s4, v255, 55
	v_readlane_b32 s5, v255, 56
	v_readlane_b32 s34, v255, 57
	v_readlane_b32 s35, v255, 58
	s_add_u32 s6, s6, 0x2bc8000
	s_addc_u32 s7, s7, 0
	s_lshl_b32 s8, s36, 27
	s_add_u32 s4, s4, s8
	s_addc_u32 s5, s5, 0
	s_add_u32 s34, s34, s8
	s_addc_u32 s35, s35, 0
	s_add_u32 s6, s6, s8
	s_addc_u32 s7, s7, 0
	s_lshl_b32 s30, s3, 14
	v_and_b32_e32 v120, 31, v200
	v_lshlrev_b32_e32 v2, 2, v120
	v_lshrrev_b32_e32 v3, 5, v200
	v_and_b32_e32 v4, 7, v200
	v_lshrrev_b32_e32 v6, 3, v200
	v_mul_u32_u24_e32 v7, 33, v3
	v_add_u32_e32 v7, v7, v120
	v_lshl_add_u32 v7, v7, 2, s30
	v_add_u32_e32 v8, 0x400, v7
	v_add_u32_e32 v9, 0x840, v7
	v_add_u32_e32 v10, 0xc40, v7
	v_add_u32_e32 v11, 0x1080, v7
	v_add_u32_e32 v12, 0x1480, v7
	v_add_u32_e32 v13, 0x18c0, v7
	v_add_u32_e32 v14, 0x1cc0, v7
	v_mul_u32_u24_e32 v120, 0x108, v4
	v_add_u32_e32 v120, v120, v6
	v_lshl_add_u32 v15, v120, 2, s30
	v_lshl_add_u32 v122, v3, 13, v2
	v_mov_b32_e32 v123, 0
	v_lshlrev_b32_e32 v124, 4, v4
	v_lshl_add_u32 v124, v6, 11, v124
	v_mov_b32_e32 v125, 0
	s_mov_b64 s[40:41], 0x20000
	s_mov_b64 s[42:43], 0x4000
	s_mov_b64 s[44:45], 0x4000
	s_waitcnt vmcnt(0) lgkmcnt(0)
; #define WAVE_LDS_SYNC() do { int _z = 0; (void)emu::wave_xchg(&_z, 4); } while (0)
; #define LAS __attribute__((address_space(3)))
; #define WAVE_LDS_SYNC() asm volatile("s_waitcnt lgkmcnt(0)" ::: "memory")
; #define NT_LOAD(p) __builtin_nontemporal_load(p)
; #define NT_STORE(v, p) __builtin_nontemporal_store((v), (p))
; DEV unsigned pk2(float lo, float hi) { return f2bf(lo) | (f2bf(hi) << 16); }
; DEV unsigned pk2(float lo, float hi) { const f32x2n_t v = {lo, hi}; return __builtin_bit_cast(unsigned, __builtin_convertvector(v, bf16x2n_t)); }
; DEV void tr_item(const float* W, int ldw, int col0, int k0, bf16_t* WT, int K, int row0, LAS float* scr, int lane) {
; #pragma unroll 8
;     for (int i = 0; i < 32; ++i) { const int kk = 2 * i + (lane >> 5); scr[kk * 33 + (lane & 31)] = NT_LOAD(&W[(size_t)(k0 + kk) * ldw + col0 + (lane & 31)]); }
;     WAVE_LDS_SYNC();
;     const int c = lane & 7;
; #pragma unroll
;     for (int j = 0; j < 4; ++j) { const int n = (lane >> 3) + 8 * j; const LAS float* s = scr + (8 * c) * 33 + n;
;         u32x4 o; o.x = pk2(s[0 * 33], s[1 * 33]); o.y = pk2(s[2 * 33], s[3 * 33]); o.z = pk2(s[4 * 33], s[5 * 33]); o.w = pk2(s[6 * 33], s[7 * 33]);
;         NT_STORE(o, (u32x4*)(WT + (size_t)(row0 + n) * K + k0 + 8 * c)); }
; DEV void phase_prologue_a(const Frame& F0) {
;     ...
;         constexpr int GU_NB = 2 * FF / 32, GU_ITEMS = 16 * GU_NB;
;         for (int it = F.gw; it < NE * GU_ITEMS; it += F.NGW) { const int e = it / GU_ITEMS, r = it % GU_ITEMS, kb = r / GU_NB, nb = r % GU_NB; const int d0 = 32 * nb, j = d0 >> 8, w = d0 & 255;
;             const float* src = (w < 128 ? GIN(I_WGATE) : GIN(I_WUP)) + ((size_t)l * NE + e) * 1024 * FF;
;             tr_item(src, FF, 128 * j + (w & 127), 64 * kb, (bf16_t*)(F.ws + WS_WGU) + ((size_t)l * NE + e) * 2 * FF * 1024, 1024, d0, scr, F.lane); }
.Lsx_loop:
	s_lshr_b32 s8, s2, 11
	s_and_b32 s9, s2, 0x7ff
	s_lshr_b32 s10, s9, 7
	s_and_b32 s9, s9, 0x7f
	s_lshl_b32 s24, s10, 19
	s_lshr_b32 s25, s9, 3
	s_lshl_b32 s25, s25, 9
	s_add_i32 s24, s24, s25
	s_and_b32 s25, s9, 3
	s_lshl_b32 s25, s25, 7
	s_add_i32 s24, s24, s25
	s_lshr_b32 s29, s8, 9
	s_lshl_b32 s28, s8, 23
	s_add_u32 s28, s28, s24
	s_addc_u32 s29, s29, 0
	s_bitcmp0_b32 s9, 2
	s_cselect_b32 s24, s4, s34
	s_cselect_b32 s25, s5, s35
	s_add_u32 s28, s28, s24
	s_addc_u32 s29, s29, s25
	s_lshl_b32 s24, s9, 16
	s_lshl_b32 s25, s10, 7
	s_add_i32 s24, s24, s25
	s_lshr_b32 s11, s8, 9
	s_lshl_b32 s10, s8, 23
	s_add_u32 s10, s10, s24
	s_addc_u32 s11, s11, 0
	s_add_u32 s10, s10, s6
	s_addc_u32 s11, s11, s7
	v_lshl_add_u64 v[16:17], s[28:29], 0, v[122:123]
	v_lshl_add_u64 v[18:19], v[16:17], 0, s[44:45]
	v_lshl_add_u64 v[20:21], v[18:19], 0, s[44:45]
	v_lshl_add_u64 v[22:23], v[20:21], 0, s[44:45]
	v_lshl_add_u64 v[24:25], v[22:23], 0, s[44:45]
	v_lshl_add_u64 v[26:27], v[24:25], 0, s[44:45]
	v_lshl_add_u64 v[28:29], v[26:27], 0, s[44:45]
	v_lshl_add_u64 v[30:31], v[28:29], 0, s[44:45]
	global_load_dword v32, v[16:17], off nt
	global_load_dword v33, v[18:19], off nt
	global_load_dword v34, v[20:21], off nt
	global_load_dword v35, v[22:23], off nt
	global_load_dword v36, v[24:25], off nt
	global_load_dword v37, v[26:27], off nt
	global_load_dword v38, v[28:29], off nt
	global_load_dword v39, v[30:31], off nt
	v_lshl_add_u64 v[16:17], v[16:17], 0, s[40:41]
	v_lshl_add_u64 v[18:19], v[18:19], 0, s[40:41]
	v_lshl_add_u64 v[20:21], v[20:21], 0, s[40:41]
	v_lshl_add_u64 v[22:23], v[22:23], 0, s[40:41]
	v_lshl_add_u64 v[24:25], v[24:25], 0, s[40:41]
	v_lshl_add_u64 v[26:27], v[26:27], 0, s[40:41]
	v_lshl_add_u64 v[28:29], v[28:29], 0, s[40:41]
	v_lshl_add_u64 v[30:31], v[30:31], 0, s[40:41]
	global_load_dword v40, v[16:17], off nt
	global_load_dword v41, v[18:19], off nt
	global_load_dword v42, v[20:21], off nt
	global_load_dword v43, v[22:23], off nt
	global_load_dword v44, v[24:25], off nt
	global_load_dword v45, v[26:27], off nt
	global_load_dword v46, v[28:29], off nt
	global_load_dword v47, v[30:31], off nt
	v_lshl_add_u64 v[16:17], v[16:17], 0, s[40:41]
	v_lshl_add_u64 v[18:19], v[18:19], 0, s[40:41]
	v_lshl_add_u64 v[20:21], v[20:21], 0, s[40:41]
	v_lshl_add_u64 v[22:23], v[22:23], 0, s[40:41]
	v_lshl_add_u64 v[24:25], v[24:25], 0, s[40:41]
	v_lshl_add_u64 v[26:27], v[26:27], 0, s[40:41]
	v_lshl_add_u64 v[28:29], v[28:29], 0, s[40:41]
	v_lshl_add_u64 v[30:31], v[30:31], 0, s[40:41]
	global_load_dword v48, v[16:17], off nt
	global_load_dword v49, v[18:19], off nt
	global_load_dword v50, v[20:21], off nt
	global_load_dword v51, v[22:23], off nt
	global_load_dword v52, v[24:25], off nt
	global_load_dword v53, v[26:27], off nt
	global_load_dword v54, v[28:29], off nt
	global_load_dword v55, v[30:31], off nt
	v_lshl_add_u64 v[16:17], v[16:17], 0, s[40:41]
	v_lshl_add_u64 v[18:19], v[18:19], 0, s[40:41]
	v_lshl_add_u64 v[20:21], v[20:21], 0, s[40:41]
	v_lshl_add_u64 v[22:23], v[22:23], 0, s[40:41]
	v_lshl_add_u64 v[24:25], v[24:25], 0, s[40:41]
	v_lshl_add_u64 v[26:27], v[26:27], 0, s[40:41]
	v_lshl_add_u64 v[28:29], v[28:29], 0, s[40:41]
	v_lshl_add_u64 v[30:31], v[30:31], 0, s[40:41]
	global_load_dword v56, v[16:17], off nt
	global_load_dword v57, v[18:19], off nt
	global_load_dword v58, v[20:21], off nt
	global_load_dword v59, v[22:23], off nt
	global_load_dword v60, v[24:25], off nt
	global_load_dword v61, v[26:27], off nt
	global_load_dword v62, v[28:29], off nt
	global_load_dword v63, v[30:31], off nt
	v_lshl_add_u64 v[64:65], s[10:11], 0, v[124:125]
	v_lshl_add_u64 v[66:67], v[64:65], 0, s[42:43]
	v_lshl_add_u64 v[68:69], v[66:67], 0, s[42:43]
	v_lshl_add_u64 v[70:71], v[68:69], 0, s[42:43]
	s_waitcnt vmcnt(30)
	ds_write2_b32 v7, v32, v33 offset1:66
	s_waitcnt vmcnt(28)
	ds_write2_b32 v7, v34, v35 offset0:132 offset1:198
	s_waitcnt vmcnt(26)
	ds_write2_b32 v8, v36, v37 offset0:8 offset1:74
	s_waitcnt vmcnt(24)
	ds_write2_b32 v8, v38, v39 offset0:140 offset1:206
	s_waitcnt vmcnt(22)
	ds_write2_b32 v9, v40, v41 offset1:66
	s_waitcnt vmcnt(20)
	ds_write2_b32 v9, v42, v43 offset0:132 offset1:198
	s_waitcnt vmcnt(18)
	ds_write2_b32 v10, v44, v45 offset0:8 offset1:74
	s_waitcnt vmcnt(16)
	ds_write2_b32 v10, v46, v47 offset0:140 offset1:206
	s_waitcnt vmcnt(14)
	ds_write2_b32 v11, v48, v49 offset1:66
	s_waitcnt vmcnt(12)
	ds_write2_b32 v11, v50, v51 offset0:132 offset1:198
	s_waitcnt vmcnt(10)
	ds_write2_b32 v12, v52, v53 offset0:8 offset1:74
	s_waitcnt vmcnt(8)
	ds_write2_b32 v12, v54, v55 offset0:140 offset1:206
	s_waitcnt vmcnt(6)
	ds_write2_b32 v13, v56, v57 offset1:66
	s_waitcnt vmcnt(4)
	ds_write2_b32 v13, v58, v59 offset0:132 offset1:198
	s_waitcnt vmcnt(2)
	ds_write2_b32 v14, v60, v61 offset0:8 offset1:74
	s_waitcnt vmcnt(0)
	ds_write2_b32 v14, v62, v63 offset0:140 offset1:206
	ds_read2_b32 v[72:73], v15 offset1:8
	ds_read2_b32 v[74:75], v15 offset0:33 offset1:41
	ds_read2_b32 v[76:77], v15 offset0:66 offset1:74
	ds_read2_b32 v[78:79], v15 offset0:99 offset1:107
	ds_read2_b32 v[80:81], v15 offset0:132 offset1:140
	ds_read2_b32 v[82:83], v15 offset0:165 offset1:173
	ds_read2_b32 v[84:85], v15 offset0:198 offset1:206
	ds_read2_b32 v[86:87], v15 offset0:231 offset1:239
	ds_read2_b32 v[88:89], v15 offset0:16 offset1:24
	ds_read2_b32 v[90:91], v15 offset0:49 offset1:57
	ds_read2_b32 v[92:93], v15 offset0:82 offset1:90
	ds_read2_b32 v[94:95], v15 offset0:115 offset1:123
	s_waitcnt lgkmcnt(4)
	v_cvt_pk_bf16_f32 v104, v72, v74
	v_cvt_pk_bf16_f32 v105, v76, v78
	v_cvt_pk_bf16_f32 v106, v80, v82
	v_cvt_pk_bf16_f32 v107, v84, v86
	v_cvt_pk_bf16_f32 v108, v73, v75
	v_cvt_pk_bf16_f32 v109, v77, v79
	v_cvt_pk_bf16_f32 v110, v81, v83
	v_cvt_pk_bf16_f32 v111, v85, v87
	ds_read2_b32 v[96:97], v15 offset0:148 offset1:156
	ds_read2_b32 v[98:99], v15 offset0:181 offset1:189
	ds_read2_b32 v[100:101], v15 offset0:214 offset1:222
	ds_read2_b32 v[102:103], v15 offset0:247 offset1:255
	global_store_dwordx4 v[64:65], v[104:107], off nt
	global_store_dwordx4 v[66:67], v[108:111], off nt
	s_waitcnt lgkmcnt(0)
	v_cvt_pk_bf16_f32 v112, v88, v90
	v_cvt_pk_bf16_f32 v113, v92, v94
	v_cvt_pk_bf16_f32 v114, v96, v98
	v_cvt_pk_bf16_f32 v115, v100, v102
	v_cvt_pk_bf16_f32 v116, v89, v91
	v_cvt_pk_bf16_f32 v117, v93, v95
	v_cvt_pk_bf16_f32 v118, v97, v99
	v_cvt_pk_bf16_f32 v119, v101, v103
	global_store_dwordx4 v[68:69], v[112:115], off nt
	global_store_dwordx4 v[70:71], v[116:119], off nt
	s_addk_i32 s2, 0x200
	s_cmp_lt_u32 s2, s101
	s_cbranch_scc1 .Lsx_loop
